# drop the cooperative-groups grid.sync at kernel entry (nothing before it needs ordering across workgroups; the custom XCD barrier does its own census)
# baseline (speedup 1.0000x reference)
_Z10hybrid_fwd4Args:
	s_load_dwordx2 s[42:43], s[0:1], 0x88
	s_mov_b64 s[84:85], s[0:1]
	s_add_u32 s6, s84, 0x88
	v_and_b32_e32 v1, 0x3ff, v0
	s_addc_u32 s7, s85, 0
	s_movk_i32 s1, 0x3ff
	v_cmp_gt_u32_e32 vcc, 8, v1
	s_and_saveexec_b64 s[4:5], vcc
	v_lshl_add_u32 v2, v1, 2, 0
	v_add_u32_e32 v2, 0x20400, v2
	v_mov_b32_e32 v3, 0
	ds_write_b32 v2, v3
	s_or_b64 exec, exec, s[4:5]
	s_load_dword s0, s[84:85], 0x90
	v_lshrrev_b32_e32 v2, 20, v0
	v_lshrrev_b32_e32 v0, 10, v0
	v_or_b32_e32 v0, v0, v2
	v_and_or_b32 v0, v0, s1, v1
	v_cmp_eq_u32_e32 vcc, 0, v0
	s_waitcnt lgkmcnt(0)
	s_barrier
	s_barrier
	s_and_saveexec_b64 s[4:5], vcc
.LBB0_12:
	s_or_b64 exec, exec, s[4:5]
	s_load_dwordx2 s[4:5], s[84:85], 0x80
	s_barrier
	s_waitcnt lgkmcnt(0)
	v_cmp_eq_u32_e64 s[10:11], 0, v1
	s_mov_b64 s[8:9], s[4:5]
	s_getreg_b32 s1, hwreg(HW_REG_XCC_ID, 0, 4)
	s_mov_b64 s[6:7], exec
	v_writelane_b32 v255, s10, 0
	s_nop 1
	v_writelane_b32 v255, s11, 1
	s_and_b64 s[10:11], s[6:7], s[10:11]
	s_mov_b64 exec, s[10:11]
	s_cbranch_execz .LBB0_14
	s_lshl_b32 s1, s1, 8
	s_and_b32 s1, s1, 0xf00
	s_add_u32 s1, s8, s1
	s_addc_u32 s3, s9, 0
	v_mov_b32_e32 v0, s1
	v_add_co_u32_e32 v2, vcc, 0x1000, v0
	v_mov_b32_e32 v0, s3
	s_nop 0
	v_addc_co_u32_e32 v3, vcc, 0, v0, vcc
	v_mov_b32_e32 v0, 1
	flat_atomic_add v[2:3], v0 offset:1024
